# GLA output units: gate loads of the 4 row groups issued together; prologue GEMV: 20 conditioning loads in flight, silu 4-wide
# baseline (speedup 1.0000x reference)
; #define LAS __attribute__((address_space(3)))
; __device__ __forceinline__ float bflo(unsigned w) { return __uint_as_float(w << 16); }
; __device__ __forceinline__ float bfhi(unsigned w) { return __uint_as_float(w & 0xffff0000u); }
; __device__ __forceinline__ unsigned cvt_pk_bf16(float lo, float hi) { unsigned r; asm volatile("v_cvt_pk_bf16_f32 %0, %1, %2" : "=v"(r) : "v"(lo), "v"(hi)); return r; }
; __device__ __forceinline__ float silu_f(float g) { return g * __builtin_amdgcn_rcpf(1.f + __expf(-g)); }
; __device__ __forceinline__ int crow16(int r, int hi) { return (r & 3) + 8 * (r >> 2) + 4 * hi; }
; __device__ __forceinline__ void gla_p3(CArgs& a, int l, int cc, int h, LAS float* L) {
;     ...
;     { const int ib = wid >> 2, eb = wid & 3; f32x16 acc = {};
; #pragma unroll
;       for (int ks = 0; ks < 4; ++ks) {
;           acc = __builtin_amdgcn_mfma_f32_32x32x16_bf16(ldfrag(B + GB_ATT, 32 * ib + r32, ks, hi), ldfrag(B + GB_VT, 32 * eb + r32, ks, hi), acc, 0, 0, 0);
;           acc = __builtin_amdgcn_mfma_f32_32x32x16_bf16(ldfrag(B + GB_QDF, 32 * ib + r32, ks, hi), ldfrag(B + GB_SFT, 32 * eb + r32, ks, hi), acc, 0, 0, 0);
;           acc = __builtin_amdgcn_mfma_f32_32x32x16_bf16(ldfrag(B + GB_QDB, 32 * ib + r32, ks, hi), ldfrag(B + GB_SBT, 32 * eb + r32, ks, hi), acc, 0, 0, 0); }
; #pragma unroll
;       for (int r = 0; r < 16; ++r) L[(32 * ib + crow16(r, hi)) * 128 + 32 * eb + r32] = acc[r]; }
;     __syncthreads();
;     const int i0 = (tid >> 5) * 4, e4 = (tid & 31) * 4;
;     bf16_t* Z = (bf16_t*)(a.ws + WS_HZ);
;     const f32x4 gn = *(const f32x4*)(a.in[I_CON] + l * 128 + e4);
; #pragma unroll
;     for (int r = 0; r < 4; ++r) { const f32x4 o = *(const LAS f32x4*)(L + (i0 + r) * 128 + e4);
;         float ss = (o.x * o.x + o.y * o.y) + (o.z * o.z + o.w * o.w);
; #pragma unroll
;         for (int m = 1; m < 32; m <<= 1) ss += __shfl_xor(ss, m);
;         const float rs = rsqrtf(ss * (1.f / 128.f) + EPS);
;         const size_t row = (size_t)cc * 64 + i0 + r;
;         const u32x2 gw = *(const u32x2*)(P + (size_t)(i0 + r) * INP + C_CG + h * 128 + e4);
;         const f32x4 y = o * rs * gn;
;         u32x2 w; w.x = cvt_pk_bf16(y.x * silu_f(bflo(gw.x)), y.y * silu_f(bfhi(gw.x))); w.y = cvt_pk_bf16(y.z * silu_f(bflo(gw.y)), y.w * silu_f(bfhi(gw.y)));
;         *(u32x2*)(Z + row * DM + 1536 + h * 128 + e4) = w; }
.LBB0_96:
	s_or_b64 exec, exec, s[42:43]
	v_ashrrev_i32_e32 v38, 8, v34
	v_lshl_or_b32 v2, v38, 5, v36
	s_movk_i32 s5, 0x90
	v_mul_lo_u32 v10, v2, s5
	s_add_i32 s5, 0, 0x15a00
	v_add3_u32 v30, s5, v10, v37
	s_waitcnt lgkmcnt(0)
	s_barrier
	v_bfe_u32 v39, v34, 6, 2
	ds_read_b128 v[2:5], v30
	v_lshl_or_b32 v6, v39, 5, v36
	v_mul_u32_u24_e32 v31, 0x90, v6
	v_add3_u32 v40, s17, v31, v37
	ds_read_b128 v[6:9], v40
	v_add3_u32 v41, 0, v10, v37
	ds_read_b128 v[18:21], v41 offset:33280
	s_waitcnt lgkmcnt(1)
	v_mfma_f32_32x32x16_bf16 v[2:17], v[2:5], v[6:9], 0
	s_add_i32 s5, 0, 0x17e00
	v_add3_u32 v42, s5, v31, v37
	ds_read_b128 v[22:25], v42
	ds_read_b128 v[26:29], v41 offset:42496
	s_add_i32 s5, 0, 0x1c600
	v_add3_u32 v37, s5, v31, v37
	v_and_b32_e32 v0, 0x7c, v0
	s_lshl_b32 s18, s4, 1
	s_waitcnt lgkmcnt(1)
	v_mfma_f32_32x32x16_bf16 v[2:17], v[18:21], v[22:25], v[2:17]
	ds_read_b128 v[18:21], v37
	s_ashr_i32 s23, s22, 31
	s_lshl_b64 s[4:5], s[22:23], 18
	s_add_u32 s4, s56, s4
	s_addc_u32 s5, s57, s5
	s_waitcnt lgkmcnt(0)
	v_mfma_f32_32x32x16_bf16 v[2:17], v[26:29], v[18:21], v[2:17]
	ds_read_b128 v[18:21], v30 offset:32
	ds_read_b128 v[22:25], v40 offset:32
	s_waitcnt lgkmcnt(0)
	v_mfma_f32_32x32x16_bf16 v[2:17], v[18:21], v[22:25], v[2:17]
	ds_read_b128 v[18:21], v41 offset:33312
	ds_read_b128 v[22:25], v42 offset:32
	s_waitcnt lgkmcnt(0)
	v_mfma_f32_32x32x16_bf16 v[2:17], v[18:21], v[22:25], v[2:17]
	ds_read_b128 v[18:21], v41 offset:42528
	ds_read_b128 v[22:25], v37 offset:32
	s_waitcnt lgkmcnt(0)
	v_mfma_f32_32x32x16_bf16 v[2:17], v[18:21], v[22:25], v[2:17]
	ds_read_b128 v[18:21], v30 offset:64
	ds_read_b128 v[22:25], v40 offset:64
	s_waitcnt lgkmcnt(0)
	v_mfma_f32_32x32x16_bf16 v[2:17], v[18:21], v[22:25], v[2:17]
	ds_read_b128 v[18:21], v41 offset:33344
	ds_read_b128 v[22:25], v42 offset:64
	s_waitcnt lgkmcnt(0)
	v_mfma_f32_32x32x16_bf16 v[2:17], v[18:21], v[22:25], v[2:17]
	ds_read_b128 v[22:25], v41 offset:42560
	ds_read_b128 v[26:29], v37 offset:64
	ds_read_b128 v[30:33], v30 offset:96
	v_lshlrev_b32_e32 v19, 11, v35
	v_ashrrev_i32_e32 v20, 3, v34
	v_lshlrev_b32_e32 v34, 14, v38
	v_lshlrev_b32_e32 v21, 2, v36
	v_lshlrev_b32_e32 v35, 7, v39
	s_waitcnt lgkmcnt(1)
	v_mfma_f32_32x32x16_bf16 v[2:17], v[22:25], v[26:29], v[2:17]
	ds_read_b128 v[22:25], v40 offset:96
	ds_read_b128 v[26:29], v41 offset:33376
	v_and_b32_e32 v18, -4, v20
	v_lshlrev_b32_e32 v36, 2, v0
	v_lshlrev_b32_e32 v0, 1, v0
	s_waitcnt lgkmcnt(1)
	v_mfma_f32_32x32x16_bf16 v[2:17], v[30:33], v[22:25], v[2:17]
	ds_read_b128 v[22:25], v42 offset:96
	v_add3_u32 v30, 0, v34, v19
	v_add3_u32 v21, v30, v35, v21
	ds_read_b128 v[30:33], v41 offset:42592
	v_ashrrev_i32_e32 v19, 31, v18
	s_waitcnt lgkmcnt(1)
	v_mfma_f32_32x32x16_bf16 v[2:17], v[26:29], v[22:25], v[2:17]
	ds_read_b128 v[22:25], v37 offset:96
	v_lshlrev_b64 v[26:27], 13, v[18:19]
	v_lshl_add_u64 v[26:27], s[20:21], 0, v[26:27]
	v_lshl_add_u64 v[26:27], v[26:27], 0, s[18:19]
	v_lshl_add_u64 v[26:27], v[26:27], 0, v[0:1]
	v_add_co_u32_e32 v26, vcc, s10, v26
	s_waitcnt lgkmcnt(0)
	v_mfma_f32_32x32x16_bf16 v[2:17], v[30:33], v[22:25], v[2:17]
	v_addc_co_u32_e32 v27, vcc, 0, v27, vcc
	s_nop 10
	ds_write2st64_b32 v21, v2, v3 offset1:2
	ds_write2st64_b32 v21, v4, v5 offset0:4 offset1:6
	ds_write2st64_b32 v21, v6, v7 offset0:16 offset1:18
	ds_write2st64_b32 v21, v8, v9 offset0:20 offset1:22
	ds_write2st64_b32 v21, v10, v11 offset0:32 offset1:34
	ds_write2st64_b32 v21, v12, v13 offset0:36 offset1:38
	ds_write2st64_b32 v21, v14, v15 offset0:48 offset1:50
	ds_write2st64_b32 v21, v16, v17 offset0:52 offset1:54
	s_waitcnt lgkmcnt(0)
	s_barrier
	global_load_dwordx2 v[10:11], v[26:27], off offset:2688
	global_load_dwordx4 v[2:5], v36, s[52:53]
	v_add_co_u32_e32 v76, vcc, 0x2000, v26
	s_nop 1
	v_addc_co_u32_e32 v77, vcc, 0, v27, vcc
	global_load_dwordx2 v[80:81], v[76:77], off offset:2688
	v_add_co_u32_e32 v76, vcc, 0x2000, v76
	s_nop 1
	v_addc_co_u32_e32 v77, vcc, 0, v77, vcc
	global_load_dwordx2 v[82:83], v[76:77], off offset:2688
	v_add_co_u32_e32 v76, vcc, 0x2000, v76
	s_nop 1
	v_addc_co_u32_e32 v77, vcc, 0, v77, vcc
	global_load_dwordx2 v[84:85], v[76:77], off offset:2688
	v_add_u32_e32 v22, 0, v36
	v_lshl_add_u32 v6, v18, 9, v22
	ds_read_b128 v[6:9], v6
	v_and_b32_e32 v12, 64, v223
	v_xor_b32_e32 v13, 1, v223
	v_add_u32_e32 v25, 64, v12
	v_cmp_lt_i32_e32 vcc, v13, v25
	s_waitcnt lgkmcnt(0)
	v_pk_mul_f32 v[14:15], v[6:7], v[6:7]
	v_xor_b32_e32 v23, 2, v223
	v_cndmask_b32_e32 v12, v223, v13, vcc
	v_lshlrev_b32_e32 v21, 2, v12
	v_pk_mul_f32 v[12:13], v[8:9], v[8:9]
	v_cmp_lt_i32_e32 vcc, v23, v25
	v_pk_mov_b32 v[16:17], v[14:15], v[12:13] op_sel:[1,0]
	v_mov_b32_e32 v15, v13
	v_pk_add_f32 v[12:13], v[16:17], v[14:15]
	v_cndmask_b32_e32 v15, v223, v23, vcc
	v_add_f32_e32 v12, v12, v13
	ds_bpermute_b32 v13, v21, v12
	v_lshlrev_b32_e32 v23, 2, v15
	v_xor_b32_e32 v24, 4, v223
	v_cmp_lt_i32_e32 vcc, v24, v25
	v_xor_b32_e32 v14, 8, v223
	s_waitcnt lgkmcnt(0)
	v_add_f32_e32 v12, v12, v13
	ds_bpermute_b32 v13, v23, v12
	v_cndmask_b32_e32 v16, v223, v24, vcc
	v_lshlrev_b32_e32 v24, 2, v16
	v_cmp_lt_i32_e64 s[40:41], v14, v25
	v_xor_b32_e32 v15, 16, v223
	s_waitcnt lgkmcnt(0)
	v_add_f32_e32 v12, v12, v13
	ds_bpermute_b32 v13, v24, v12
	v_cndmask_b32_e64 v14, v223, v14, s[40:41]
	v_cmp_lt_i32_e32 vcc, v15, v25
	v_lshlrev_b32_e32 v25, 2, v14
	s_waitcnt lgkmcnt(0)
	v_add_f32_e32 v14, v12, v13
	ds_bpermute_b32 v16, v25, v14
	v_cndmask_b32_e32 v15, v223, v15, vcc
	v_lshlrev_b32_e32 v26, 2, v15
	v_or_b32_e32 v12, 1, v18
	v_ashrrev_i32_e32 v13, 31, v12
	s_waitcnt lgkmcnt(0)
; #define LAS __attribute__((address_space(3)))
; __device__ __forceinline__ float bflo(unsigned w) { return __uint_as_float(w << 16); }
; __device__ __forceinline__ float bfhi(unsigned w) { return __uint_as_float(w & 0xffff0000u); }
; __device__ __forceinline__ unsigned cvt_pk_bf16(float lo, float hi) { unsigned r; asm volatile("v_cvt_pk_bf16_f32 %0, %1, %2" : "=v"(r) : "v"(lo), "v"(hi)); return r; }
; __device__ __forceinline__ float silu_f(float g) { return g * __builtin_amdgcn_rcpf(1.f + __expf(-g)); }
; __device__ __forceinline__ void gla_p3(CArgs& a, int l, int cc, int h, LAS float* L) {
;     ...
;     for (int r = 0; r < 4; ++r) { const f32x4 o = *(const LAS f32x4*)(L + (i0 + r) * 128 + e4);
;         float ss = (o.x * o.x + o.y * o.y) + (o.z * o.z + o.w * o.w);
; #pragma unroll
;         for (int m = 1; m < 32; m <<= 1) ss += __shfl_xor(ss, m);
;         const float rs = rsqrtf(ss * (1.f / 128.f) + EPS);
;         const size_t row = (size_t)cc * 64 + i0 + r;
;         const u32x2 gw = *(const u32x2*)(P + (size_t)(i0 + r) * INP + C_CG + h * 128 + e4);
;         const f32x4 y = o * rs * gn;
;         u32x2 w; w.x = cvt_pk_bf16(y.x * silu_f(bflo(gw.x)), y.y * silu_f(bfhi(gw.x))); w.y = cvt_pk_bf16(y.z * silu_f(bflo(gw.y)), y.w * silu_f(bfhi(gw.y)));
;         *(u32x2*)(Z + row * DM + 1536 + h * 128 + e4) = w; }
	v_add_f32_e32 v16, v14, v16
	ds_bpermute_b32 v17, v26, v16
	v_lshlrev_b64 v[14:15], 13, v[12:13]
	v_lshl_add_u64 v[14:15], s[20:21], 0, v[14:15]
	v_lshl_add_u64 v[14:15], v[14:15], 0, s[18:19]
	v_lshl_add_u64 v[14:15], v[14:15], 0, v[0:1]
	s_waitcnt lgkmcnt(0)
	v_add_f32_e32 v13, v16, v17
	v_fmamk_f32 v13, v13, 0x3c000000, v216
	v_cmp_gt_f32_e32 vcc, s26, v13
	v_mul_f32_e32 v16, 0x4b800000, v13
	s_nop 0
	v_cndmask_b32_e32 v13, v13, v16, vcc
	v_rsq_f32_e32 v13, v13
	v_add_co_u32_e64 v16, s[40:41], s10, v14
	v_mul_f32_e32 v14, 0x45800000, v13
	v_cndmask_b32_e32 v14, v13, v14, vcc
	v_pk_mul_f32 v[6:7], v[6:7], v[14:15] op_sel_hi:[1,0]
	v_pk_mul_f32 v[8:9], v[8:9], v[14:15] op_sel_hi:[1,0]
	v_addc_co_u32_e64 v17, s[40:41], 0, v15, s[40:41]
	s_waitcnt vmcnt(1)
	v_lshlrev_b32_e32 v13, 16, v10
	v_and_b32_e32 v10, 0xffff0000, v10
	v_lshlrev_b32_e32 v14, 16, v11
	v_and_b32_e32 v11, 0xffff0000, v11
	v_mul_f32_e32 v15, 0xbfb8aa3b, v13
	v_mul_f32_e32 v27, 0xbfb8aa3b, v10
	v_mul_f32_e32 v28, 0xbfb8aa3b, v14
	v_mul_f32_e32 v29, 0xbfb8aa3b, v11
	v_exp_f32_e32 v15, v15
	v_exp_f32_e32 v27, v27
	v_exp_f32_e32 v28, v28
	v_exp_f32_e32 v29, v29
	v_add_f32_e32 v15, 1.0, v15
	v_add_f32_e32 v27, 1.0, v27
	v_add_f32_e32 v28, 1.0, v28
	v_add_f32_e32 v29, 1.0, v29
	v_rcp_f32_e32 v15, v15
	v_rcp_f32_e32 v27, v27
	v_rcp_f32_e32 v28, v28
	v_rcp_f32_e32 v29, v29
	s_waitcnt vmcnt(0)
	v_pk_mul_f32 v[8:9], v[4:5], v[8:9]
	v_pk_mul_f32 v[6:7], v[2:3], v[6:7]
	v_mul_f32_e32 v13, v15, v13
	v_mul_f32_e32 v10, v27, v10
	v_mul_f32_e32 v14, v28, v14
	v_mul_f32_e32 v11, v29, v11
	v_mul_f32_e32 v6, v13, v6
	v_mul_f32_e32 v7, v10, v7
	v_mul_f32_e32 v8, v14, v8
	v_mul_f32_e32 v9, v11, v9
	v_cvt_pk_bf16_f32 v14, v6, v7
	v_cvt_pk_bf16_f32 v15, v8, v9
	v_mov_b64_e32 v[16:17], v[80:81]
	v_lshl_add_u32 v6, v12, 9, v22
	ds_read_b128 v[6:9], v6
	s_waitcnt lgkmcnt(0)
	v_pk_mul_f32 v[10:11], v[8:9], v[8:9]
	v_pk_mul_f32 v[12:13], v[6:7], v[6:7]
	s_nop 0
	v_pk_mov_b32 v[28:29], v[12:13], v[10:11] op_sel:[1,0]
	v_mov_b32_e32 v13, v11
	v_pk_add_f32 v[10:11], v[28:29], v[12:13]
	v_or_b32_e32 v12, 2, v18
	v_add_f32_e32 v10, v10, v11
	ds_bpermute_b32 v11, v21, v10
	v_ashrrev_i32_e32 v13, 31, v12
	s_waitcnt lgkmcnt(0)
	v_add_f32_e32 v27, v10, v11
	ds_bpermute_b32 v28, v23, v27
	v_lshlrev_b64 v[10:11], 12, v[18:19]
	v_lshlrev_b64 v[18:19], 13, v[12:13]
	v_lshl_add_u64 v[10:11], s[4:5], 0, v[10:11]
	v_lshl_add_u64 v[10:11], v[10:11], 0, s[18:19]
	s_waitcnt lgkmcnt(0)
	v_add_f32_e32 v27, v27, v28
	ds_bpermute_b32 v28, v24, v27
	v_lshl_add_u64 v[10:11], v[10:11], 0, v[0:1]
	s_mov_b32 s4, 0xb900000
	v_lshl_add_u64 v[18:19], s[20:21], 0, v[18:19]
	v_lshl_add_u64 v[18:19], v[18:19], 0, s[18:19]
	s_waitcnt lgkmcnt(0)
	v_add_f32_e32 v13, v27, v28
	ds_bpermute_b32 v27, v25, v13
	v_add_co_u32_e32 v28, vcc, s4, v10
	v_lshl_add_u64 v[18:19], v[18:19], 0, v[0:1]
	s_nop 0
	v_addc_co_u32_e32 v29, vcc, 0, v11, vcc
	s_waitcnt lgkmcnt(0)
	v_add_f32_e32 v13, v13, v27
	ds_bpermute_b32 v27, v26, v13
	global_store_dwordx2 v[28:29], v[14:15], off offset:3072
	v_add_co_u32_e32 v18, vcc, s10, v18
	s_mov_b32 s4, 0xb901000
	s_waitcnt lgkmcnt(0)
	v_add_f32_e32 v13, v13, v27
	v_fmamk_f32 v13, v13, 0x3c000000, v216
	v_cmp_gt_f32_e64 s[40:41], s26, v13
	v_mul_f32_e32 v27, 0x4b800000, v13
	v_addc_co_u32_e32 v19, vcc, 0, v19, vcc
	v_cndmask_b32_e64 v13, v13, v27, s[40:41]
	v_rsq_f32_e32 v13, v13
	s_nop 0
	v_mul_f32_e32 v14, 0x45800000, v13
	v_cndmask_b32_e64 v14, v13, v14, s[40:41]
	v_pk_mul_f32 v[6:7], v[6:7], v[14:15] op_sel_hi:[1,0]
	v_pk_mul_f32 v[8:9], v[8:9], v[14:15] op_sel_hi:[1,0]
	v_pk_mul_f32 v[6:7], v[2:3], v[6:7]
	v_pk_mul_f32 v[8:9], v[4:5], v[8:9]
	s_waitcnt vmcnt(1)
	v_lshlrev_b32_e32 v13, 16, v16
	v_and_b32_e32 v14, 0xffff0000, v16
	v_and_b32_e32 v16, 0xffff0000, v17
	v_lshlrev_b32_e32 v15, 16, v17
	v_mul_f32_e32 v29, 0xbfb8aa3b, v16
	v_mul_f32_e32 v17, 0xbfb8aa3b, v13
	v_mul_f32_e32 v27, 0xbfb8aa3b, v14
	v_mul_f32_e32 v28, 0xbfb8aa3b, v15
	v_exp_f32_e32 v29, v29
	v_exp_f32_e32 v17, v17
	v_exp_f32_e32 v27, v27
	v_exp_f32_e32 v28, v28
	v_add_f32_e32 v29, 1.0, v29
	v_add_f32_e32 v17, 1.0, v17
	v_add_f32_e32 v27, 1.0, v27
	v_add_f32_e32 v28, 1.0, v28
	v_rcp_f32_e32 v29, v29
	v_rcp_f32_e32 v17, v17
	v_rcp_f32_e32 v27, v27
	v_rcp_f32_e32 v28, v28
	v_mul_f32_e32 v16, v29, v16
	v_mul_f32_e32 v13, v17, v13
	v_mul_f32_e32 v14, v27, v14
	v_mul_f32_e32 v15, v28, v15
	v_mul_f32_e32 v9, v16, v9
	v_mul_f32_e32 v6, v13, v6
	v_mul_f32_e32 v7, v14, v7
	v_mul_f32_e32 v13, v15, v8
	v_cvt_pk_bf16_f32 v8, v6, v7
	v_cvt_pk_bf16_f32 v9, v13, v9
	v_mov_b64_e32 v[16:17], v[82:83]
	v_lshl_add_u32 v6, v12, 9, v22
	ds_read_b128 v[12:15], v6
	s_waitcnt lgkmcnt(0)
; #define LAS __attribute__((address_space(3)))
; __device__ __forceinline__ float bflo(unsigned w) { return __uint_as_float(w << 16); }
; __device__ __forceinline__ float bfhi(unsigned w) { return __uint_as_float(w & 0xffff0000u); }
; __device__ __forceinline__ unsigned cvt_pk_bf16(float lo, float hi) { unsigned r; asm volatile("v_cvt_pk_bf16_f32 %0, %1, %2" : "=v"(r) : "v"(lo), "v"(hi)); return r; }
; __device__ __forceinline__ float silu_f(float g) { return g * __builtin_amdgcn_rcpf(1.f + __expf(-g)); }
; __device__ __forceinline__ void gla_p3(CArgs& a, int l, int cc, int h, LAS float* L) {
;     ...
;     for (int r = 0; r < 4; ++r) { const f32x4 o = *(const LAS f32x4*)(L + (i0 + r) * 128 + e4);
;         float ss = (o.x * o.x + o.y * o.y) + (o.z * o.z + o.w * o.w);
; #pragma unroll
;         for (int m = 1; m < 32; m <<= 1) ss += __shfl_xor(ss, m);
;         const float rs = rsqrtf(ss * (1.f / 128.f) + EPS);
;         const size_t row = (size_t)cc * 64 + i0 + r;
;         const u32x2 gw = *(const u32x2*)(P + (size_t)(i0 + r) * INP + C_CG + h * 128 + e4);
;         const f32x4 y = o * rs * gn;
;         u32x2 w; w.x = cvt_pk_bf16(y.x * silu_f(bflo(gw.x)), y.y * silu_f(bfhi(gw.x))); w.y = cvt_pk_bf16(y.z * silu_f(bflo(gw.y)), y.w * silu_f(bfhi(gw.y)));
;         *(u32x2*)(Z + row * DM + 1536 + h * 128 + e4) = w; }
	v_pk_mul_f32 v[6:7], v[14:15], v[14:15]
	v_pk_mul_f32 v[18:19], v[12:13], v[12:13]
	s_nop 0
	v_pk_mov_b32 v[28:29], v[18:19], v[6:7] op_sel:[1,0]
	v_mov_b32_e32 v19, v7
	v_pk_add_f32 v[6:7], v[28:29], v[18:19]
	s_nop 0
	v_add_f32_e32 v6, v6, v7
	ds_bpermute_b32 v7, v21, v6
	s_waitcnt lgkmcnt(0)
	v_add_f32_e32 v6, v6, v7
	ds_bpermute_b32 v7, v23, v6
	s_waitcnt lgkmcnt(0)
	v_add_f32_e32 v27, v6, v7
	ds_bpermute_b32 v28, v24, v27
	v_or_b32_e32 v6, 3, v20
	v_ashrrev_i32_e32 v7, 31, v6
	v_lshlrev_b64 v[18:19], 13, v[6:7]
	v_lshl_add_u64 v[18:19], s[20:21], 0, v[18:19]
	s_waitcnt lgkmcnt(0)
	v_add_f32_e32 v7, v27, v28
	ds_bpermute_b32 v20, v25, v7
	v_lshl_add_u64 v[18:19], v[18:19], 0, s[18:19]
	v_lshl_add_u64 v[18:19], v[18:19], 0, v[0:1]
	v_add_co_u32_e32 v28, vcc, s4, v10
	s_waitcnt lgkmcnt(0)
	v_add_f32_e32 v0, v7, v20
	ds_bpermute_b32 v7, v26, v0
	v_addc_co_u32_e32 v29, vcc, 0, v11, vcc
	global_store_dwordx2 v[28:29], v[8:9], off offset:3072
	v_add_co_u32_e64 v18, s[40:41], s10, v18
	s_waitcnt lgkmcnt(0)
	v_add_f32_e32 v0, v0, v7
	v_fmamk_f32 v0, v0, 0x3c000000, v216
	v_cmp_gt_f32_e32 vcc, s26, v0
	v_mul_f32_e32 v7, 0x4b800000, v0
	v_addc_co_u32_e64 v19, s[40:41], 0, v19, s[40:41]
	v_cndmask_b32_e32 v0, v0, v7, vcc
	v_rsq_f32_e32 v0, v0
	s_mov_b32 s4, 0xb902000
	v_mul_f32_e32 v7, 0x45800000, v0
	v_cndmask_b32_e32 v0, v0, v7, vcc
	v_pk_mul_f32 v[8:9], v[12:13], v[0:1] op_sel_hi:[1,0]
	v_pk_mul_f32 v[12:13], v[14:15], v[0:1] op_sel_hi:[1,0]
	v_pk_mul_f32 v[8:9], v[2:3], v[8:9]
	v_pk_mul_f32 v[12:13], v[4:5], v[12:13]
	s_waitcnt vmcnt(1)
	v_lshlrev_b32_e32 v0, 16, v16
	v_and_b32_e32 v7, 0xffff0000, v16
	v_lshlrev_b32_e32 v14, 16, v17
	v_and_b32_e32 v15, 0xffff0000, v17
	v_mul_f32_e32 v16, 0xbfb8aa3b, v0
	v_mul_f32_e32 v17, 0xbfb8aa3b, v7
	v_mul_f32_e32 v20, 0xbfb8aa3b, v14
	v_mul_f32_e32 v27, 0xbfb8aa3b, v15
	v_exp_f32_e32 v16, v16
	v_exp_f32_e32 v17, v17
	v_exp_f32_e32 v20, v20
	v_exp_f32_e32 v27, v27
	v_add_f32_e32 v16, 1.0, v16
	v_add_f32_e32 v17, 1.0, v17
	v_add_f32_e32 v20, 1.0, v20
	v_add_f32_e32 v27, 1.0, v27
	v_rcp_f32_e32 v16, v16
	v_rcp_f32_e32 v17, v17
	v_rcp_f32_e32 v20, v20
	v_rcp_f32_e32 v27, v27
	v_mul_f32_e32 v0, v16, v0
	v_mul_f32_e32 v7, v17, v7
	v_mul_f32_e32 v14, v20, v14
	v_mul_f32_e32 v15, v27, v15
	v_mul_f32_e32 v0, v0, v8
	v_mul_f32_e32 v7, v7, v9
	v_mul_f32_e32 v8, v14, v12
	v_mul_f32_e32 v9, v15, v13
	v_cvt_pk_bf16_f32 v12, v0, v7
	v_cvt_pk_bf16_f32 v13, v8, v9
	v_mov_b64_e32 v[14:15], v[84:85]
	v_lshl_add_u32 v0, v6, 9, v22
	ds_read_b128 v[6:9], v0
	s_waitcnt lgkmcnt(0)
	v_pk_mul_f32 v[16:17], v[8:9], v[8:9]
	v_pk_mul_f32 v[18:19], v[6:7], v[6:7]
	s_nop 0
	v_pk_mov_b32 v[28:29], v[18:19], v[16:17] op_sel:[1,0]
	v_mov_b32_e32 v19, v17
	v_pk_add_f32 v[16:17], v[28:29], v[18:19]
	s_nop 0
	v_add_f32_e32 v0, v16, v17
	ds_bpermute_b32 v16, v21, v0
	s_waitcnt lgkmcnt(0)
	v_add_f32_e32 v0, v0, v16
	ds_bpermute_b32 v16, v23, v0
	s_waitcnt lgkmcnt(0)
	v_add_f32_e32 v0, v0, v16
	ds_bpermute_b32 v16, v24, v0
	s_waitcnt lgkmcnt(0)
	v_add_f32_e32 v0, v0, v16
	ds_bpermute_b32 v17, v25, v0
	v_add_co_u32_e64 v16, s[40:41], s4, v10
	v_add_co_u32_e32 v10, vcc, 0xb903000, v10
	s_waitcnt lgkmcnt(0)
	v_add_f32_e32 v0, v0, v17
	ds_bpermute_b32 v18, v26, v0
	v_addc_co_u32_e64 v17, s[40:41], 0, v11, s[40:41]
	global_store_dwordx2 v[16:17], v[12:13], off offset:3072
	v_addc_co_u32_e32 v11, vcc, 0, v11, vcc
	s_waitcnt lgkmcnt(0)
	v_add_f32_e32 v0, v0, v18
	v_fmamk_f32 v0, v0, 0x3c000000, v216
	v_cmp_gt_f32_e64 s[40:41], s26, v0
	v_mul_f32_e32 v18, 0x4b800000, v0
	s_nop 0
	v_cndmask_b32_e64 v0, v0, v18, s[40:41]
	v_rsq_f32_e32 v0, v0
	s_nop 0
	v_mul_f32_e32 v12, 0x45800000, v0
	v_cndmask_b32_e64 v0, v0, v12, s[40:41]
	v_pk_mul_f32 v[6:7], v[6:7], v[0:1] op_sel_hi:[1,0]
	v_pk_mul_f32 v[8:9], v[8:9], v[0:1] op_sel_hi:[1,0]
	v_pk_mul_f32 v[2:3], v[2:3], v[6:7]
	v_pk_mul_f32 v[4:5], v[4:5], v[8:9]
	s_waitcnt vmcnt(1)
	v_lshlrev_b32_e32 v0, 16, v14
	v_and_b32_e32 v6, 0xffff0000, v14
	v_lshlrev_b32_e32 v7, 16, v15
	v_and_b32_e32 v8, 0xffff0000, v15
	v_mul_f32_e32 v9, 0xbfb8aa3b, v0
	v_mul_f32_e32 v12, 0xbfb8aa3b, v6
	v_mul_f32_e32 v13, 0xbfb8aa3b, v7
	v_mul_f32_e32 v14, 0xbfb8aa3b, v8
	v_exp_f32_e32 v9, v9
	v_exp_f32_e32 v12, v12
	v_exp_f32_e32 v13, v13
	v_exp_f32_e32 v14, v14
	v_add_f32_e32 v9, 1.0, v9
	v_add_f32_e32 v12, 1.0, v12
	v_add_f32_e32 v13, 1.0, v13
	v_add_f32_e32 v14, 1.0, v14
	v_rcp_f32_e32 v9, v9
	v_rcp_f32_e32 v12, v12
	v_rcp_f32_e32 v13, v13
	v_rcp_f32_e32 v14, v14
	v_mul_f32_e32 v0, v9, v0
	v_mul_f32_e32 v6, v12, v6
	v_mul_f32_e32 v7, v13, v7
	v_mul_f32_e32 v8, v14, v8
	v_mul_f32_e32 v0, v0, v2
	v_mul_f32_e32 v2, v6, v3
	v_mul_f32_e32 v3, v7, v4
	v_mul_f32_e32 v4, v8, v5
	v_cvt_pk_bf16_f32 v2, v0, v2
	v_cvt_pk_bf16_f32 v3, v3, v4
	global_store_dwordx2 v[10:11], v[2:3], off offset:3072
	s_branch .LBB0_70

; __device__ __forceinline__ float silu_f(float g) { return g * __builtin_amdgcn_rcpf(1.f + __expf(-g)); }
; __device__ __forceinline__ void phase_prologue(CArgs& a, LAS unsigned char* lds) {
;     ...
;         for (int q = 0; q < 4; ++q) { const int k = wid * 256 + q * 64 + lane;
; #pragma unroll
;             for (int v = 0; v < 5; ++v) { const float cv = (v < 4) ? a.in[I_C][v * DM + k] : a.in[I_CCTX][k]; scr[v * 256 + q * 64 + lane] = silu_f(cv); } }
;         asm volatile("s_waitcnt lgkmcnt(0)" ::: "memory");
.LBB0_348:
	s_waitcnt lgkmcnt(0)
	s_barrier
	global_load_dword v48, v[10:11], off
	global_load_dword v49, v[12:13], off
	global_load_dword v50, v[14:15], off
	global_load_dword v51, v[16:17], off
	global_load_dword v52, v[8:9], off
	global_load_dword v53, v[10:11], off offset:256
	global_load_dword v54, v[18:19], off
	global_load_dword v55, v[20:21], off
	global_load_dword v56, v[22:23], off
	global_load_dword v57, v[8:9], off offset:256
	global_load_dword v58, v[10:11], off offset:512
	global_load_dword v59, v[24:25], off
	global_load_dword v60, v[26:27], off
	global_load_dword v61, v[28:29], off
	global_load_dword v62, v[8:9], off offset:512
	global_load_dword v63, v[10:11], off offset:768
	global_load_dword v64, v[30:31], off
	global_load_dword v65, v[32:33], off
	global_load_dword v66, v[34:35], off
	global_load_dword v67, v[8:9], off offset:768
	s_mul_hi_i32 s4, s12, 0x2aaaaaab
	s_lshr_b32 s5, s4, 31
	s_ashr_i32 s13, s4, 4
	s_add_i32 s13, s13, s5
	s_mul_i32 s4, s13, 0x60
	s_sub_i32 s6, s12, s4
	s_lshl_b32 s40, s6, 7
	s_ashr_i32 s41, s40, 31
	s_mov_b32 s8, 0
	s_waitcnt vmcnt(16)
	v_mul_f32_e32 v68, 0xbfb8aa3b, v48
	v_mul_f32_e32 v69, 0xbfb8aa3b, v49
	v_mul_f32_e32 v70, 0xbfb8aa3b, v50
	v_mul_f32_e32 v71, 0xbfb8aa3b, v51
	v_exp_f32_e32 v68, v68
	v_exp_f32_e32 v69, v69
	v_exp_f32_e32 v70, v70
	v_exp_f32_e32 v71, v71
	v_add_f32_e32 v68, 1.0, v68
	v_add_f32_e32 v69, 1.0, v69
	v_add_f32_e32 v70, 1.0, v70
	v_add_f32_e32 v71, 1.0, v71
	v_rcp_f32_e32 v68, v68
	v_rcp_f32_e32 v69, v69
	v_rcp_f32_e32 v70, v70
	v_rcp_f32_e32 v71, v71
	v_mul_f32_e32 v48, v48, v68
	v_mul_f32_e32 v49, v49, v69
	v_mul_f32_e32 v50, v50, v70
	v_mul_f32_e32 v51, v51, v71
	s_waitcnt vmcnt(12)
	v_mul_f32_e32 v68, 0xbfb8aa3b, v52
	v_mul_f32_e32 v69, 0xbfb8aa3b, v53
	v_mul_f32_e32 v70, 0xbfb8aa3b, v54
	v_mul_f32_e32 v71, 0xbfb8aa3b, v55
	v_exp_f32_e32 v68, v68
	v_exp_f32_e32 v69, v69
	v_exp_f32_e32 v70, v70
	v_exp_f32_e32 v71, v71
	v_add_f32_e32 v68, 1.0, v68
	v_add_f32_e32 v69, 1.0, v69
	v_add_f32_e32 v70, 1.0, v70
	v_add_f32_e32 v71, 1.0, v71
	v_rcp_f32_e32 v68, v68
	v_rcp_f32_e32 v69, v69
	v_rcp_f32_e32 v70, v70
	v_rcp_f32_e32 v71, v71
	v_mul_f32_e32 v52, v52, v68
	v_mul_f32_e32 v53, v53, v69
	v_mul_f32_e32 v54, v54, v70
	v_mul_f32_e32 v55, v55, v71
	s_waitcnt vmcnt(8)
	v_mul_f32_e32 v68, 0xbfb8aa3b, v56
	v_mul_f32_e32 v69, 0xbfb8aa3b, v57
	v_mul_f32_e32 v70, 0xbfb8aa3b, v58
	v_mul_f32_e32 v71, 0xbfb8aa3b, v59
	v_exp_f32_e32 v68, v68
	v_exp_f32_e32 v69, v69
	v_exp_f32_e32 v70, v70
	v_exp_f32_e32 v71, v71
	v_add_f32_e32 v68, 1.0, v68
	v_add_f32_e32 v69, 1.0, v69
	v_add_f32_e32 v70, 1.0, v70
	v_add_f32_e32 v71, 1.0, v71
	v_rcp_f32_e32 v68, v68
	v_rcp_f32_e32 v69, v69
	v_rcp_f32_e32 v70, v70
	v_rcp_f32_e32 v71, v71
	v_mul_f32_e32 v56, v56, v68
	v_mul_f32_e32 v57, v57, v69
	v_mul_f32_e32 v58, v58, v70
	v_mul_f32_e32 v59, v59, v71
	s_waitcnt vmcnt(4)
	v_mul_f32_e32 v68, 0xbfb8aa3b, v60
	v_mul_f32_e32 v69, 0xbfb8aa3b, v61
	v_mul_f32_e32 v70, 0xbfb8aa3b, v62
	v_mul_f32_e32 v71, 0xbfb8aa3b, v63
	v_exp_f32_e32 v68, v68
	v_exp_f32_e32 v69, v69
	v_exp_f32_e32 v70, v70
	v_exp_f32_e32 v71, v71
	v_add_f32_e32 v68, 1.0, v68
	v_add_f32_e32 v69, 1.0, v69
	v_add_f32_e32 v70, 1.0, v70
	v_add_f32_e32 v71, 1.0, v71
	v_rcp_f32_e32 v68, v68
	v_rcp_f32_e32 v69, v69
	v_rcp_f32_e32 v70, v70
	v_rcp_f32_e32 v71, v71
	v_mul_f32_e32 v60, v60, v68
	v_mul_f32_e32 v61, v61, v69
	v_mul_f32_e32 v62, v62, v70
	v_mul_f32_e32 v63, v63, v71
	s_waitcnt vmcnt(0)
	v_mul_f32_e32 v68, 0xbfb8aa3b, v64
	v_mul_f32_e32 v69, 0xbfb8aa3b, v65
	v_mul_f32_e32 v70, 0xbfb8aa3b, v66
	v_mul_f32_e32 v71, 0xbfb8aa3b, v67
	v_exp_f32_e32 v68, v68
	v_exp_f32_e32 v69, v69
	v_exp_f32_e32 v70, v70
	v_exp_f32_e32 v71, v71
	v_add_f32_e32 v68, 1.0, v68
	v_add_f32_e32 v69, 1.0, v69
	v_add_f32_e32 v70, 1.0, v70
	v_add_f32_e32 v71, 1.0, v71
	v_rcp_f32_e32 v68, v68
	v_rcp_f32_e32 v69, v69
	v_rcp_f32_e32 v70, v70
	v_rcp_f32_e32 v71, v71
	v_mul_f32_e32 v64, v64, v68
	v_mul_f32_e32 v65, v65, v69
	v_mul_f32_e32 v66, v66, v70
	v_mul_f32_e32 v67, v67, v71
	ds_write2st64_b32 v177, v48, v53 offset1:1
	ds_write2st64_b32 v177, v49, v54 offset0:4 offset1:5
	ds_write2st64_b32 v177, v50, v55 offset0:8 offset1:9
	ds_write2st64_b32 v177, v51, v56 offset0:12 offset1:13
	ds_write2st64_b32 v177, v52, v57 offset0:16 offset1:17
	ds_write2st64_b32 v177, v58, v63 offset0:2 offset1:3
	ds_write2st64_b32 v177, v59, v64 offset0:6 offset1:7
	ds_write2st64_b32 v177, v60, v65 offset0:10 offset1:11
	ds_write2st64_b32 v177, v61, v66 offset0:14 offset1:15
	ds_write2st64_b32 v177, v62, v67 offset0:18 offset1:19
	v_mov_b32_e32 v38, 0
	v_mov_b32_e32 v40, v38
	v_mov_b32_e32 v41, v38
	v_mov_b32_e32 v42, v38
	v_mov_b32_e32 v43, v38
	v_mov_b32_e32 v44, v38
	v_mov_b32_e32 v45, v38
	v_mov_b32_e32 v46, v38
	v_mov_b32_e32 v47, v38
	v_mov_b32_e32 v39, v38
	s_waitcnt lgkmcnt(0)
	v_mad_i64_i32 v[36:37], s[4:5], s13, v226, v[4:5]
	v_lshl_add_u64 v[36:37], s[40:41], 2, v[36:37]
	v_lshlrev_b32_e32 v0, 2, v6
	v_lshl_add_u64 v[36:37], v[36:37], 0, v[0:1]
